# combo2 + MoBA gating: second k-mean load group issued early and lane^32 half-sums via permlane32_swap
# speedup vs baseline: 1.0039x; 1.0006x over previous
.LBB0_478:
	s_bitcmp0_b32 s13, 0
	s_cselect_b32 s3, s5, s6
	s_add_i32 s2, s3, s2
	s_cmpk_gt_i32 s2, 0x7ff
	s_cbranch_scc1 .LBB0_477
	v_mov_b32_e32 v37, v206
	v_mov_b32_e32 v0, v206
	s_ashr_i32 s3, s2, 7
	s_sub_i32 s3, 15, s3
	v_ashrrev_i32_e32 v0, 1, v0
	s_lshl_b32 s2, s2, 4
	s_and_b32 s15, s3, 15
	v_and_b32_e32 v0, 0xffffffe0, v0
	s_and_b32 s2, s2, 0x7f0
	v_and_b32_e32 v36, 31, v37
	v_lshl_add_u32 v103, s15, 7, v0
	s_or_b32 s14, s2, s3
	v_or_b32_e32 v2, v103, v36
	s_lshr_b32 s76, s14, 8
	v_ashrrev_i32_e32 v3, 31, v2
	s_lshl_b64 s[2:3], s[76:77], 21
	v_lshlrev_b64 v[2:3], 10, v[2:3]
	s_bfe_u32 s22, s14, 0x40004
	v_lshl_add_u64 v[98:99], v[2:3], 0, s[2:3]
	v_lshl_add_u64 v[2:3], v[98:99], 1, s[36:37]
	s_lshl_b32 s2, s22, 7
	s_mov_b32 s3, s77
	v_and_b32_e32 v0, 32, v37
	v_lshl_add_u64 v[2:3], v[2:3], 0, s[2:3]
	v_lshlrev_b32_e32 v100, 1, v0
	v_mov_b32_e32 v101, v1
	v_lshl_add_u64 v[2:3], v[2:3], 0, v[100:101]
	global_load_dwordx4 v[66:69], v[2:3], off offset:48
	global_load_dwordx4 v[70:73], v[2:3], off offset:32
	global_load_dwordx4 v[74:77], v[2:3], off offset:16
	global_load_dwordx4 v[78:81], v[2:3], off
	s_lshl_b64 s[2:3], s[76:77], 15
	s_add_u32 s2, s7, s2
	s_addc_u32 s3, s8, s3
	s_lshl_b32 s16, s22, 11
	s_add_u32 s2, s2, s16
	v_ashrrev_i32_e32 v38, 8, v103
	s_addc_u32 s3, s3, 0
	v_lshlrev_b32_e32 v0, 2, v0
	v_lshl_add_u64 v[2:3], s[2:3], 0, v[0:1]
	v_cmp_lt_i32_e32 vcc, 0, v38
	v_mov_b32_e32 v0, 0
	v_mov_b32_e32 v39, 0
	s_waitcnt vmcnt(3)
	v_lshlrev_b32_e32 v5, 16, v68
	s_waitcnt vmcnt(2)
	v_lshlrev_b32_e32 v13, 16, v72
	s_waitcnt vmcnt(1)
	v_lshlrev_b32_e32 v21, 16, v76
	s_waitcnt vmcnt(0)
	v_lshlrev_b32_e32 v29, 16, v80
	v_lshlrev_b32_e32 v28, 16, v78
	v_and_b32_e32 v35, 0xffff0000, v80
	v_and_b32_e32 v34, 0xffff0000, v78
	v_lshlrev_b32_e32 v33, 16, v81
	v_lshlrev_b32_e32 v32, 16, v79
	v_and_b32_e32 v31, 0xffff0000, v81
	v_and_b32_e32 v30, 0xffff0000, v79
	v_lshlrev_b32_e32 v20, 16, v74
	v_and_b32_e32 v27, 0xffff0000, v76
	v_and_b32_e32 v26, 0xffff0000, v74
	v_lshlrev_b32_e32 v25, 16, v77
	v_lshlrev_b32_e32 v24, 16, v75
	v_and_b32_e32 v23, 0xffff0000, v77
	v_and_b32_e32 v22, 0xffff0000, v75
	v_lshlrev_b32_e32 v12, 16, v70
	v_and_b32_e32 v19, 0xffff0000, v72
	v_and_b32_e32 v18, 0xffff0000, v70
	v_lshlrev_b32_e32 v17, 16, v73
	v_lshlrev_b32_e32 v16, 16, v71
	v_and_b32_e32 v15, 0xffff0000, v73
	v_and_b32_e32 v14, 0xffff0000, v71
	v_lshlrev_b32_e32 v4, 16, v66
	v_and_b32_e32 v11, 0xffff0000, v68
	v_and_b32_e32 v10, 0xffff0000, v66
	v_lshlrev_b32_e32 v9, 16, v69
	v_lshlrev_b32_e32 v8, 16, v67
	v_and_b32_e32 v7, 0xffff0000, v69
	v_and_b32_e32 v6, 0xffff0000, v67
	s_and_saveexec_b64 s[2:3], vcc
	s_cbranch_execz .LBB0_481
	global_load_dwordx4 v[40:43], v[2:3], off offset:48
	global_load_dwordx4 v[44:47], v[2:3], off offset:32
	global_load_dwordx4 v[48:51], v[2:3], off offset:16
	global_load_dwordx4 v[52:55], v[2:3], off
	global_load_dwordx4 v[82:85], v[2:3], off offset:112
	global_load_dwordx4 v[86:89], v[2:3], off offset:96
	global_load_dwordx4 v[90:93], v[2:3], off offset:80
	global_load_dwordx4 v[94:97], v[2:3], off offset:64
	v_cmp_lt_i32_e32 vcc, v211, v210
	s_waitcnt vmcnt(5)
	v_mov_b32_e32 v57, v48
	s_waitcnt vmcnt(4)
	v_mov_b32_e32 v48, v53
	v_mov_b32_e32 v56, v52
	v_pk_mul_f32 v[48:49], v[48:49], v[34:35]
	v_mov_b32_e32 v52, v54
	v_pk_fma_f32 v[48:49], v[56:57], v[28:29], v[48:49]
	v_mov_b32_e32 v53, v50
	v_pk_fma_f32 v[48:49], v[52:53], v[32:33], v[48:49]
	v_mov_b32_e32 v50, v55
	v_pk_fma_f32 v[48:49], v[50:51], v[30:31], v[48:49]
	s_nop 0
	v_add_f32_e32 v39, 0, v48
	v_add_f32_e32 v39, v39, v49
	v_mov_b32_e32 v49, v40
	v_mov_b32_e32 v40, v45
	v_mov_b32_e32 v48, v44
	v_pk_mul_f32 v[40:41], v[40:41], v[26:27]
	v_mov_b32_e32 v44, v46
	v_pk_fma_f32 v[40:41], v[48:49], v[20:21], v[40:41]
	v_mov_b32_e32 v45, v42
	v_pk_fma_f32 v[40:41], v[44:45], v[24:25], v[40:41]
	v_mov_b32_e32 v42, v47
	v_pk_fma_f32 v[40:41], v[42:43], v[22:23], v[40:41]
	s_nop 0
	v_add_f32_e32 v39, v39, v40
	v_add_f32_e32 v39, v39, v41
	s_waitcnt vmcnt(0)
	v_mov_b64_e32 v[40:41], v[82:83]
	v_mov_b64_e32 v[42:43], v[84:85]
	v_mov_b64_e32 v[44:45], v[86:87]
	v_mov_b64_e32 v[46:47], v[88:89]
	v_mov_b64_e32 v[48:49], v[90:91]
	v_mov_b64_e32 v[50:51], v[92:93]
	v_mov_b64_e32 v[52:53], v[94:95]
	v_mov_b64_e32 v[54:55], v[96:97]
	s_waitcnt vmcnt(1)
	v_mov_b32_e32 v57, v48
	s_waitcnt vmcnt(0)
	v_mov_b32_e32 v48, v53
	v_mov_b32_e32 v56, v52
	v_pk_mul_f32 v[48:49], v[48:49], v[18:19]
	v_mov_b32_e32 v52, v54
	v_pk_fma_f32 v[48:49], v[56:57], v[12:13], v[48:49]
	v_mov_b32_e32 v53, v50
	v_pk_fma_f32 v[48:49], v[52:53], v[16:17], v[48:49]
	v_mov_b32_e32 v50, v55
	v_pk_fma_f32 v[48:49], v[50:51], v[14:15], v[48:49]
	s_nop 0
	v_add_f32_e32 v39, v39, v48
	v_add_f32_e32 v39, v39, v49
	v_mov_b32_e32 v49, v40
	v_mov_b32_e32 v40, v45
	v_mov_b32_e32 v48, v44
	v_pk_mul_f32 v[40:41], v[40:41], v[10:11]
	v_mov_b32_e32 v44, v46
	v_pk_fma_f32 v[40:41], v[48:49], v[4:5], v[40:41]
	v_mov_b32_e32 v45, v42
	v_pk_fma_f32 v[40:41], v[44:45], v[8:9], v[40:41]
	v_mov_b32_e32 v42, v47
	v_pk_fma_f32 v[40:41], v[42:43], v[6:7], v[40:41]
	s_nop 0
	v_add_f32_e32 v39, v39, v40
	v_cndmask_b32_e32 v40, v209, v211, vcc
	v_add_f32_e32 v39, v39, v41
	v_mov_b32_e32 v40, v39
	s_nop 1
	v_permlane32_swap_b32_e32 v40, v39
	v_add_f32_e32 v39, v39, v40
.LBB0_481:
	s_or_b64 exec, exec, s[2:3]
	v_cmp_lt_i32_e32 vcc, 1, v38
	s_and_saveexec_b64 s[2:3], vcc
	s_cbranch_execz .LBB0_483
	global_load_dwordx4 v[40:43], v[2:3], off offset:304
	global_load_dwordx4 v[44:47], v[2:3], off offset:288
	global_load_dwordx4 v[48:51], v[2:3], off offset:272
	global_load_dwordx4 v[52:55], v[2:3], off offset:256
	global_load_dwordx4 v[82:85], v[2:3], off offset:368
	global_load_dwordx4 v[86:89], v[2:3], off offset:352
	global_load_dwordx4 v[90:93], v[2:3], off offset:336
	global_load_dwordx4 v[94:97], v[2:3], off offset:320
	v_cmp_lt_i32_e32 vcc, v211, v210
	s_waitcnt vmcnt(5)
	v_mov_b32_e32 v57, v48
	s_waitcnt vmcnt(4)
	v_mov_b32_e32 v48, v53
	v_mov_b32_e32 v56, v52
	v_pk_mul_f32 v[48:49], v[48:49], v[34:35]
	v_mov_b32_e32 v52, v54
	v_pk_fma_f32 v[48:49], v[56:57], v[28:29], v[48:49]
	v_mov_b32_e32 v53, v50
	v_pk_fma_f32 v[48:49], v[52:53], v[32:33], v[48:49]
	v_mov_b32_e32 v50, v55
	v_pk_fma_f32 v[48:49], v[50:51], v[30:31], v[48:49]
	s_nop 0
	v_add_f32_e32 v0, 0, v48
	v_add_f32_e32 v0, v0, v49
	v_mov_b32_e32 v49, v40
	v_mov_b32_e32 v40, v45
	v_mov_b32_e32 v48, v44
	v_pk_mul_f32 v[40:41], v[40:41], v[26:27]
	v_mov_b32_e32 v44, v46
	v_pk_fma_f32 v[40:41], v[48:49], v[20:21], v[40:41]
	v_mov_b32_e32 v45, v42
	v_pk_fma_f32 v[40:41], v[44:45], v[24:25], v[40:41]
	v_mov_b32_e32 v42, v47
	v_pk_fma_f32 v[40:41], v[42:43], v[22:23], v[40:41]
	s_nop 0
	v_add_f32_e32 v0, v0, v40
	v_add_f32_e32 v0, v0, v41
	s_waitcnt vmcnt(0)
	v_mov_b64_e32 v[40:41], v[82:83]
	v_mov_b64_e32 v[42:43], v[84:85]
	v_mov_b64_e32 v[44:45], v[86:87]
	v_mov_b64_e32 v[46:47], v[88:89]
	v_mov_b64_e32 v[48:49], v[90:91]
	v_mov_b64_e32 v[50:51], v[92:93]
	v_mov_b64_e32 v[52:53], v[94:95]
	v_mov_b64_e32 v[54:55], v[96:97]
	s_waitcnt vmcnt(1)
	v_mov_b32_e32 v57, v48
	s_waitcnt vmcnt(0)
	v_mov_b32_e32 v48, v53
	v_mov_b32_e32 v56, v52
	v_pk_mul_f32 v[48:49], v[48:49], v[18:19]
	v_mov_b32_e32 v52, v54
	v_pk_fma_f32 v[48:49], v[56:57], v[12:13], v[48:49]
	v_mov_b32_e32 v53, v50
	v_pk_fma_f32 v[48:49], v[52:53], v[16:17], v[48:49]
	v_mov_b32_e32 v50, v55
	v_pk_fma_f32 v[48:49], v[50:51], v[14:15], v[48:49]
	s_nop 0
	v_add_f32_e32 v0, v0, v48
	v_add_f32_e32 v0, v0, v49
	v_mov_b32_e32 v49, v40
	v_mov_b32_e32 v40, v45
	v_mov_b32_e32 v48, v44
	v_pk_mul_f32 v[40:41], v[40:41], v[10:11]
	v_mov_b32_e32 v44, v46
	v_pk_fma_f32 v[40:41], v[48:49], v[4:5], v[40:41]
	v_mov_b32_e32 v45, v42
	v_pk_fma_f32 v[40:41], v[44:45], v[8:9], v[40:41]
	v_mov_b32_e32 v42, v47
	v_pk_fma_f32 v[40:41], v[42:43], v[6:7], v[40:41]
	s_nop 0
	v_add_f32_e32 v0, v0, v40
	v_cndmask_b32_e32 v40, v209, v211, vcc
	v_add_f32_e32 v0, v0, v41
	v_mov_b32_e32 v40, v0
	s_nop 1
	v_permlane32_swap_b32_e32 v40, v0
	v_add_f32_e32 v0, v0, v40
.LBB0_483:
	s_or_b64 exec, exec, s[2:3]
	v_cmp_lt_i32_e32 vcc, 2, v38
	v_mov_b32_e32 v40, 0
	v_mov_b32_e32 v41, 0
	s_and_saveexec_b64 s[2:3], vcc
	s_cbranch_execz .LBB0_485
	global_load_dwordx4 v[42:45], v[2:3], off offset:560
	global_load_dwordx4 v[46:49], v[2:3], off offset:544
	global_load_dwordx4 v[50:53], v[2:3], off offset:528
	global_load_dwordx4 v[54:57], v[2:3], off offset:512
	global_load_dwordx4 v[82:85], v[2:3], off offset:624
	global_load_dwordx4 v[86:89], v[2:3], off offset:608
	global_load_dwordx4 v[90:93], v[2:3], off offset:592
	global_load_dwordx4 v[94:97], v[2:3], off offset:576
	v_cmp_lt_i32_e32 vcc, v211, v210
	s_waitcnt vmcnt(5)
	v_mov_b32_e32 v59, v50
	s_waitcnt vmcnt(4)
	v_mov_b32_e32 v50, v55
	v_mov_b32_e32 v58, v54
	v_pk_mul_f32 v[50:51], v[50:51], v[34:35]
	v_mov_b32_e32 v54, v56
	v_pk_fma_f32 v[50:51], v[58:59], v[28:29], v[50:51]
	v_mov_b32_e32 v55, v52
	v_pk_fma_f32 v[50:51], v[54:55], v[32:33], v[50:51]
	v_mov_b32_e32 v52, v57
	v_pk_fma_f32 v[50:51], v[52:53], v[30:31], v[50:51]
	s_nop 0
	v_add_f32_e32 v41, 0, v50
	v_add_f32_e32 v41, v41, v51
	v_mov_b32_e32 v51, v42
	v_mov_b32_e32 v42, v47
	v_mov_b32_e32 v50, v46
	v_pk_mul_f32 v[42:43], v[42:43], v[26:27]
	v_mov_b32_e32 v46, v48
	v_pk_fma_f32 v[42:43], v[50:51], v[20:21], v[42:43]
	v_mov_b32_e32 v47, v44
	v_pk_fma_f32 v[42:43], v[46:47], v[24:25], v[42:43]
	v_mov_b32_e32 v44, v49
	v_pk_fma_f32 v[42:43], v[44:45], v[22:23], v[42:43]
	s_nop 0
	v_add_f32_e32 v41, v41, v42
	v_add_f32_e32 v41, v41, v43
	s_waitcnt vmcnt(0)
	v_mov_b64_e32 v[42:43], v[82:83]
	v_mov_b64_e32 v[44:45], v[84:85]
	v_mov_b64_e32 v[46:47], v[86:87]
	v_mov_b64_e32 v[48:49], v[88:89]
	v_mov_b64_e32 v[50:51], v[90:91]
	v_mov_b64_e32 v[52:53], v[92:93]
	v_mov_b64_e32 v[54:55], v[94:95]
	v_mov_b64_e32 v[56:57], v[96:97]
	s_waitcnt vmcnt(1)
	v_mov_b32_e32 v59, v50
	s_waitcnt vmcnt(0)
	v_mov_b32_e32 v50, v55
	v_mov_b32_e32 v58, v54
	v_pk_mul_f32 v[50:51], v[50:51], v[18:19]
	v_mov_b32_e32 v54, v56
	v_pk_fma_f32 v[50:51], v[58:59], v[12:13], v[50:51]
	v_mov_b32_e32 v55, v52
	v_pk_fma_f32 v[50:51], v[54:55], v[16:17], v[50:51]
	v_mov_b32_e32 v52, v57
	v_pk_fma_f32 v[50:51], v[52:53], v[14:15], v[50:51]
	s_nop 0
	v_add_f32_e32 v41, v41, v50
	v_add_f32_e32 v41, v41, v51
	v_mov_b32_e32 v51, v42
	v_mov_b32_e32 v42, v47
	v_mov_b32_e32 v50, v46
	v_pk_mul_f32 v[42:43], v[42:43], v[10:11]
	v_mov_b32_e32 v46, v48
	v_pk_fma_f32 v[42:43], v[50:51], v[4:5], v[42:43]
	v_mov_b32_e32 v47, v44
	v_pk_fma_f32 v[42:43], v[46:47], v[8:9], v[42:43]
	v_mov_b32_e32 v44, v49
	v_pk_fma_f32 v[42:43], v[44:45], v[6:7], v[42:43]
	s_nop 0
	v_add_f32_e32 v41, v41, v42
	v_cndmask_b32_e32 v42, v209, v211, vcc
	v_add_f32_e32 v41, v41, v43
	v_mov_b32_e32 v42, v41
	s_nop 1
	v_permlane32_swap_b32_e32 v42, v41
	v_add_f32_e32 v41, v41, v42
.LBB0_485:
	s_or_b64 exec, exec, s[2:3]
	v_cmp_lt_i32_e32 vcc, 3, v38
	s_and_saveexec_b64 s[2:3], vcc
	s_cbranch_execz .LBB0_487
	global_load_dwordx4 v[42:45], v[2:3], off offset:816
	global_load_dwordx4 v[46:49], v[2:3], off offset:800
	global_load_dwordx4 v[50:53], v[2:3], off offset:784
	global_load_dwordx4 v[54:57], v[2:3], off offset:768
	global_load_dwordx4 v[82:85], v[2:3], off offset:880
	global_load_dwordx4 v[86:89], v[2:3], off offset:864
	global_load_dwordx4 v[90:93], v[2:3], off offset:848
	global_load_dwordx4 v[94:97], v[2:3], off offset:832
	v_cmp_lt_i32_e32 vcc, v211, v210
	s_waitcnt vmcnt(5)
	v_mov_b32_e32 v59, v50
	s_waitcnt vmcnt(4)
	v_mov_b32_e32 v50, v55
	v_mov_b32_e32 v58, v54
	v_pk_mul_f32 v[50:51], v[50:51], v[34:35]
	v_mov_b32_e32 v54, v56
	v_pk_fma_f32 v[50:51], v[58:59], v[28:29], v[50:51]
	v_mov_b32_e32 v55, v52
	v_pk_fma_f32 v[50:51], v[54:55], v[32:33], v[50:51]
	v_mov_b32_e32 v52, v57
	v_pk_fma_f32 v[50:51], v[52:53], v[30:31], v[50:51]
	s_nop 0
	v_add_f32_e32 v40, 0, v50
	v_add_f32_e32 v40, v40, v51
	v_mov_b32_e32 v51, v42
	v_mov_b32_e32 v42, v47
	v_mov_b32_e32 v50, v46
	v_pk_mul_f32 v[42:43], v[42:43], v[26:27]
	v_mov_b32_e32 v46, v48
	v_pk_fma_f32 v[42:43], v[50:51], v[20:21], v[42:43]
	v_mov_b32_e32 v47, v44
	v_pk_fma_f32 v[42:43], v[46:47], v[24:25], v[42:43]
	v_mov_b32_e32 v44, v49
	v_pk_fma_f32 v[42:43], v[44:45], v[22:23], v[42:43]
	s_nop 0
	v_add_f32_e32 v40, v40, v42
	v_add_f32_e32 v40, v40, v43
	s_waitcnt vmcnt(0)
	v_mov_b64_e32 v[42:43], v[82:83]
	v_mov_b64_e32 v[44:45], v[84:85]
	v_mov_b64_e32 v[46:47], v[86:87]
	v_mov_b64_e32 v[48:49], v[88:89]
	v_mov_b64_e32 v[50:51], v[90:91]
	v_mov_b64_e32 v[52:53], v[92:93]
	v_mov_b64_e32 v[54:55], v[94:95]
	v_mov_b64_e32 v[56:57], v[96:97]
	s_waitcnt vmcnt(1)
	v_mov_b32_e32 v59, v50
	s_waitcnt vmcnt(0)
	v_mov_b32_e32 v50, v55
	v_mov_b32_e32 v58, v54
	v_pk_mul_f32 v[50:51], v[50:51], v[18:19]
	v_mov_b32_e32 v54, v56
	v_pk_fma_f32 v[50:51], v[58:59], v[12:13], v[50:51]
	v_mov_b32_e32 v55, v52
	v_pk_fma_f32 v[50:51], v[54:55], v[16:17], v[50:51]
	v_mov_b32_e32 v52, v57
	v_pk_fma_f32 v[50:51], v[52:53], v[14:15], v[50:51]
	s_nop 0
	v_add_f32_e32 v40, v40, v50
	v_add_f32_e32 v40, v40, v51
	v_mov_b32_e32 v51, v42
	v_mov_b32_e32 v42, v47
	v_mov_b32_e32 v50, v46
	v_pk_mul_f32 v[42:43], v[42:43], v[10:11]
	v_mov_b32_e32 v46, v48
	v_pk_fma_f32 v[42:43], v[50:51], v[4:5], v[42:43]
	v_mov_b32_e32 v47, v44
	v_pk_fma_f32 v[42:43], v[46:47], v[8:9], v[42:43]
	v_mov_b32_e32 v44, v49
	v_pk_fma_f32 v[42:43], v[44:45], v[6:7], v[42:43]
	s_nop 0
	v_add_f32_e32 v40, v40, v42
	v_cndmask_b32_e32 v42, v209, v211, vcc
	v_add_f32_e32 v40, v40, v43
	v_mov_b32_e32 v42, v40
	s_nop 1
	v_permlane32_swap_b32_e32 v42, v40
	v_add_f32_e32 v40, v40, v42
.LBB0_487:
	s_or_b64 exec, exec, s[2:3]
	v_cmp_lt_i32_e32 vcc, 4, v38
	v_mov_b32_e32 v42, 0
	v_mov_b32_e32 v43, 0
	s_and_saveexec_b64 s[2:3], vcc
	s_cbranch_execz .LBB0_489
	global_load_dwordx4 v[44:47], v[2:3], off offset:1072
	global_load_dwordx4 v[48:51], v[2:3], off offset:1056
	global_load_dwordx4 v[52:55], v[2:3], off offset:1040
	global_load_dwordx4 v[56:59], v[2:3], off offset:1024
	global_load_dwordx4 v[82:85], v[2:3], off offset:1136
	global_load_dwordx4 v[86:89], v[2:3], off offset:1120
	global_load_dwordx4 v[90:93], v[2:3], off offset:1104
	global_load_dwordx4 v[94:97], v[2:3], off offset:1088
	v_cmp_lt_i32_e64 s[38:39], v211, v210
	s_waitcnt vmcnt(5)
	v_mov_b32_e32 v61, v52
	s_waitcnt vmcnt(4)
	v_mov_b32_e32 v52, v57
	v_mov_b32_e32 v60, v56
	v_pk_mul_f32 v[52:53], v[52:53], v[34:35]
	v_mov_b32_e32 v56, v58
	v_pk_fma_f32 v[52:53], v[60:61], v[28:29], v[52:53]
	v_mov_b32_e32 v57, v54
	v_pk_fma_f32 v[52:53], v[56:57], v[32:33], v[52:53]
	v_mov_b32_e32 v54, v59
	v_pk_fma_f32 v[52:53], v[54:55], v[30:31], v[52:53]
	s_nop 0
	v_add_f32_e32 v43, 0, v52
	v_add_f32_e32 v43, v43, v53
	v_mov_b32_e32 v53, v44
	v_mov_b32_e32 v44, v49
	v_mov_b32_e32 v52, v48
	v_pk_mul_f32 v[44:45], v[44:45], v[26:27]
	v_mov_b32_e32 v48, v50
	v_pk_fma_f32 v[44:45], v[52:53], v[20:21], v[44:45]
	v_mov_b32_e32 v49, v46
	v_pk_fma_f32 v[44:45], v[48:49], v[24:25], v[44:45]
	v_mov_b32_e32 v46, v51
	v_pk_fma_f32 v[44:45], v[46:47], v[22:23], v[44:45]
	s_nop 0
	v_add_f32_e32 v43, v43, v44
	v_add_f32_e32 v43, v43, v45
	s_waitcnt vmcnt(0)
	v_mov_b64_e32 v[44:45], v[82:83]
	v_mov_b64_e32 v[46:47], v[84:85]
	v_mov_b64_e32 v[48:49], v[86:87]
	v_mov_b64_e32 v[50:51], v[88:89]
	v_mov_b64_e32 v[52:53], v[90:91]
	v_mov_b64_e32 v[54:55], v[92:93]
	v_mov_b64_e32 v[56:57], v[94:95]
	v_mov_b64_e32 v[58:59], v[96:97]
	s_waitcnt vmcnt(1)
	v_mov_b32_e32 v61, v52
	s_waitcnt vmcnt(0)
	v_mov_b32_e32 v52, v57
	v_mov_b32_e32 v60, v56
	v_pk_mul_f32 v[52:53], v[52:53], v[18:19]
	v_mov_b32_e32 v56, v58
	v_pk_fma_f32 v[52:53], v[60:61], v[12:13], v[52:53]
	v_mov_b32_e32 v57, v54
	v_pk_fma_f32 v[52:53], v[56:57], v[16:17], v[52:53]
	v_mov_b32_e32 v54, v59
	v_pk_fma_f32 v[52:53], v[54:55], v[14:15], v[52:53]
	s_nop 0
	v_add_f32_e32 v43, v43, v52
	v_add_f32_e32 v43, v43, v53
	v_mov_b32_e32 v53, v44
	v_mov_b32_e32 v44, v49
	v_mov_b32_e32 v52, v48
	v_pk_mul_f32 v[44:45], v[44:45], v[10:11]
	v_mov_b32_e32 v48, v50
	v_pk_fma_f32 v[44:45], v[52:53], v[4:5], v[44:45]
	v_mov_b32_e32 v49, v46
	v_pk_fma_f32 v[44:45], v[48:49], v[8:9], v[44:45]
	v_mov_b32_e32 v46, v51
	v_pk_fma_f32 v[44:45], v[46:47], v[6:7], v[44:45]
	s_nop 0
	v_add_f32_e32 v43, v43, v44
	v_cndmask_b32_e64 v44, v209, v211, s[38:39]
	v_add_f32_e32 v43, v43, v45
	v_mov_b32_e32 v44, v43
	s_nop 1
	v_permlane32_swap_b32_e32 v44, v43
	v_add_f32_e32 v43, v43, v44
.LBB0_489:
	s_or_b64 exec, exec, s[2:3]
	v_cmp_lt_i32_e64 s[38:39], 5, v38
	s_and_saveexec_b64 s[2:3], s[38:39]
	s_cbranch_execz .LBB0_491
	global_load_dwordx4 v[44:47], v[2:3], off offset:1328
	global_load_dwordx4 v[48:51], v[2:3], off offset:1312
	global_load_dwordx4 v[52:55], v[2:3], off offset:1296
	global_load_dwordx4 v[56:59], v[2:3], off offset:1280
	global_load_dwordx4 v[82:85], v[2:3], off offset:1392
	global_load_dwordx4 v[86:89], v[2:3], off offset:1376
	global_load_dwordx4 v[90:93], v[2:3], off offset:1360
	global_load_dwordx4 v[94:97], v[2:3], off offset:1344
	v_cmp_lt_i32_e64 s[40:41], v211, v210
	s_waitcnt vmcnt(5)
	v_mov_b32_e32 v61, v52
	s_waitcnt vmcnt(4)
	v_mov_b32_e32 v52, v57
	v_mov_b32_e32 v60, v56
	v_pk_mul_f32 v[52:53], v[52:53], v[34:35]
	v_mov_b32_e32 v56, v58
	v_pk_fma_f32 v[52:53], v[60:61], v[28:29], v[52:53]
	v_mov_b32_e32 v57, v54
	v_pk_fma_f32 v[52:53], v[56:57], v[32:33], v[52:53]
	v_mov_b32_e32 v54, v59
	v_pk_fma_f32 v[52:53], v[54:55], v[30:31], v[52:53]
	s_nop 0
	v_add_f32_e32 v42, 0, v52
	v_add_f32_e32 v42, v42, v53
	v_mov_b32_e32 v53, v44
	v_mov_b32_e32 v44, v49
	v_mov_b32_e32 v52, v48
	v_pk_mul_f32 v[44:45], v[44:45], v[26:27]
	v_mov_b32_e32 v48, v50
	v_pk_fma_f32 v[44:45], v[52:53], v[20:21], v[44:45]
	v_mov_b32_e32 v49, v46
	v_pk_fma_f32 v[44:45], v[48:49], v[24:25], v[44:45]
	v_mov_b32_e32 v46, v51
	v_pk_fma_f32 v[44:45], v[46:47], v[22:23], v[44:45]
	s_nop 0
	v_add_f32_e32 v42, v42, v44
	v_add_f32_e32 v42, v42, v45
	s_waitcnt vmcnt(0)
	v_mov_b64_e32 v[44:45], v[82:83]
	v_mov_b64_e32 v[46:47], v[84:85]
	v_mov_b64_e32 v[48:49], v[86:87]
	v_mov_b64_e32 v[50:51], v[88:89]
	v_mov_b64_e32 v[52:53], v[90:91]
	v_mov_b64_e32 v[54:55], v[92:93]
	v_mov_b64_e32 v[56:57], v[94:95]
	v_mov_b64_e32 v[58:59], v[96:97]
	s_waitcnt vmcnt(1)
	v_mov_b32_e32 v61, v52
	s_waitcnt vmcnt(0)
	v_mov_b32_e32 v52, v57
	v_mov_b32_e32 v60, v56
	v_pk_mul_f32 v[52:53], v[52:53], v[18:19]
	v_mov_b32_e32 v56, v58
	v_pk_fma_f32 v[52:53], v[60:61], v[12:13], v[52:53]
	v_mov_b32_e32 v57, v54
	v_pk_fma_f32 v[52:53], v[56:57], v[16:17], v[52:53]
	v_mov_b32_e32 v54, v59
	v_pk_fma_f32 v[52:53], v[54:55], v[14:15], v[52:53]
	s_nop 0
	v_add_f32_e32 v42, v42, v52
	v_add_f32_e32 v42, v42, v53
	v_mov_b32_e32 v53, v44
	v_mov_b32_e32 v44, v49
	v_mov_b32_e32 v52, v48
	v_pk_mul_f32 v[44:45], v[44:45], v[10:11]
	v_mov_b32_e32 v48, v50
	v_pk_fma_f32 v[44:45], v[52:53], v[4:5], v[44:45]
	v_mov_b32_e32 v49, v46
	v_pk_fma_f32 v[44:45], v[48:49], v[8:9], v[44:45]
	v_mov_b32_e32 v46, v51
	v_pk_fma_f32 v[44:45], v[46:47], v[6:7], v[44:45]
	s_nop 0
	v_add_f32_e32 v42, v42, v44
	v_cndmask_b32_e64 v44, v209, v211, s[40:41]
	v_add_f32_e32 v42, v42, v45
	v_mov_b32_e32 v44, v42
	s_nop 1
	v_permlane32_swap_b32_e32 v44, v42
	v_add_f32_e32 v42, v42, v44
.LBB0_491:
	s_or_b64 exec, exec, s[2:3]
	v_cmp_lt_i32_e64 s[40:41], 6, v38
	v_mov_b32_e32 v44, 0
	s_and_saveexec_b64 s[2:3], s[40:41]
	s_cbranch_execz .LBB0_493
	global_load_dwordx4 v[44:47], v[2:3], off offset:1584
	global_load_dwordx4 v[48:51], v[2:3], off offset:1568
	global_load_dwordx4 v[52:55], v[2:3], off offset:1552
	global_load_dwordx4 v[56:59], v[2:3], off offset:1536
	global_load_dwordx4 v[82:85], v[2:3], off offset:1648
	global_load_dwordx4 v[86:89], v[2:3], off offset:1632
	global_load_dwordx4 v[90:93], v[2:3], off offset:1616
	global_load_dwordx4 v[94:97], v[2:3], off offset:1600
	v_cmp_lt_i32_e64 s[42:43], v211, v210
	s_waitcnt vmcnt(5)
	v_mov_b32_e32 v61, v52
	s_waitcnt vmcnt(4)
	v_mov_b32_e32 v52, v57
	v_mov_b32_e32 v60, v56
	v_pk_mul_f32 v[34:35], v[52:53], v[34:35]
	s_nop 0
	v_pk_fma_f32 v[28:29], v[60:61], v[28:29], v[34:35]
	v_mov_b32_e32 v34, v58
	v_mov_b32_e32 v35, v54
	v_pk_fma_f32 v[28:29], v[34:35], v[32:33], v[28:29]
	v_mov_b32_e32 v54, v59
	v_pk_fma_f32 v[28:29], v[54:55], v[30:31], v[28:29]
	s_nop 0
	v_add_f32_e32 v28, 0, v28
	v_add_f32_e32 v30, v28, v29
	v_mov_b32_e32 v29, v44
	v_mov_b32_e32 v44, v49
	v_mov_b32_e32 v28, v48
	v_pk_mul_f32 v[26:27], v[44:45], v[26:27]
	s_nop 0
	v_pk_fma_f32 v[20:21], v[28:29], v[20:21], v[26:27]
	v_mov_b32_e32 v26, v50
	v_mov_b32_e32 v27, v46
	v_pk_fma_f32 v[20:21], v[26:27], v[24:25], v[20:21]
	v_mov_b32_e32 v46, v51
	v_pk_fma_f32 v[20:21], v[46:47], v[22:23], v[20:21]
	s_nop 0
	v_add_f32_e32 v20, v30, v20
	v_add_f32_e32 v44, v20, v21
	s_waitcnt vmcnt(0)
	v_mov_b64_e32 v[20:21], v[82:83]
	v_mov_b64_e32 v[22:23], v[84:85]
	v_mov_b64_e32 v[24:25], v[86:87]
	v_mov_b64_e32 v[26:27], v[88:89]
	v_mov_b64_e32 v[28:29], v[90:91]
	v_mov_b64_e32 v[30:31], v[92:93]
	v_mov_b64_e32 v[32:33], v[94:95]
	v_mov_b64_e32 v[34:35], v[96:97]
	s_waitcnt vmcnt(1)
	v_mov_b32_e32 v3, v28
	s_waitcnt vmcnt(0)
	v_mov_b32_e32 v28, v33
	v_mov_b32_e32 v2, v32
	v_pk_mul_f32 v[18:19], v[28:29], v[18:19]
	s_nop 0
	v_pk_fma_f32 v[2:3], v[2:3], v[12:13], v[18:19]
	v_mov_b32_e32 v12, v34
	v_mov_b32_e32 v13, v30
	v_pk_fma_f32 v[2:3], v[12:13], v[16:17], v[2:3]
	v_mov_b32_e32 v30, v35
	v_pk_fma_f32 v[2:3], v[30:31], v[14:15], v[2:3]
	s_nop 0
	v_add_f32_e32 v2, v44, v2
	v_add_f32_e32 v12, v2, v3
	v_mov_b32_e32 v3, v20
	v_mov_b32_e32 v20, v25
	v_mov_b32_e32 v2, v24
	v_pk_mul_f32 v[10:11], v[20:21], v[10:11]
	s_nop 0
	v_pk_fma_f32 v[2:3], v[2:3], v[4:5], v[10:11]
	v_mov_b32_e32 v4, v26
	v_mov_b32_e32 v5, v22
	v_pk_fma_f32 v[2:3], v[4:5], v[8:9], v[2:3]
	v_mov_b32_e32 v22, v27
	v_pk_fma_f32 v[2:3], v[22:23], v[6:7], v[2:3]
	s_nop 0
	v_add_f32_e32 v2, v12, v2
	v_add_f32_e32 v2, v2, v3
	v_cndmask_b32_e64 v3, v209, v211, s[42:43]
	v_lshlrev_b32_e32 v3, 2, v3
	ds_bpermute_b32 v3, v3, v2
	s_waitcnt lgkmcnt(0)
	v_add_f32_e32 v44, v2, v3
